# v63 + code placement: every GEMM K-loop head aligned to 256 bytes
# baseline (speedup 1.0000x reference)
.LBB0_307:
	s_ashr_i32 s37, s36, 31
	s_ashr_i32 s31, s30, 31
	s_lshl_b64 s[0:1], s[36:37], 20
	s_lshl_b64 s[14:15], s[30:31], 20
	v_readlane_b32 s7, v254, 54
	s_add_u32 s38, s7, s0
	v_readlane_b32 s0, v254, 56
	s_addc_u32 s39, s0, s1
	s_add_u32 s40, s2, s14
	s_addc_u32 s41, s3, s15
	s_and_b64 s[0:1], s[34:35], exec
	s_cselect_b32 s0, s39, s45
	s_cselect_b32 s1, s38, s44
	s_cselect_b32 s7, s41, s47
	s_cselect_b32 s14, s40, s46
	s_add_u32 s44, s44, 0x80080
	s_addc_u32 s45, s45, 0
	s_add_u32 s15, s46, 0x100
	v_mov_b32_e32 v2, 0
	s_addc_u32 s31, s47, 0
	s_mov_b32 s37, -2
	v_mov_b32_e32 v3, v2
	v_mov_b32_e32 v4, v2
	v_mov_b32_e32 v5, v2
	v_mov_b32_e32 v6, v2
	v_mov_b32_e32 v7, v2
	v_mov_b32_e32 v8, v2
	v_mov_b32_e32 v9, v2
	v_mov_b32_e32 v18, v2
	v_mov_b32_e32 v19, v2
	v_mov_b32_e32 v20, v2
	v_mov_b32_e32 v21, v2
	s_waitcnt vmcnt(0)
	v_mov_b32_e32 v22, v2
	v_mov_b32_e32 v23, v2
	v_mov_b32_e32 v24, v2
	v_mov_b32_e32 v25, v2
	v_mov_b32_e32 v34, v2
	v_mov_b32_e32 v35, v2
	v_mov_b32_e32 v36, v2
	v_mov_b32_e32 v37, v2
	v_mov_b32_e32 v38, v2
	v_mov_b32_e32 v39, v2
	v_mov_b32_e32 v40, v2
	v_mov_b32_e32 v41, v2
	v_mov_b32_e32 v50, v2
	v_mov_b32_e32 v51, v2
	v_mov_b32_e32 v52, v2
	v_mov_b32_e32 v53, v2
	v_mov_b32_e32 v54, v2
	v_mov_b32_e32 v55, v2
	v_mov_b32_e32 v56, v2
	v_mov_b32_e32 v57, v2
	v_mov_b32_e32 v10, v2
	v_mov_b32_e32 v11, v2
	v_mov_b32_e32 v12, v2
	v_mov_b32_e32 v13, v2
	v_mov_b32_e32 v14, v2
	v_mov_b32_e32 v15, v2
	v_mov_b32_e32 v16, v2
	v_mov_b32_e32 v17, v2
	v_mov_b32_e32 v26, v2
	v_mov_b32_e32 v27, v2
	v_mov_b32_e32 v28, v2
	v_mov_b32_e32 v29, v2
	v_mov_b32_e32 v30, v2
	v_mov_b32_e32 v31, v2
	v_mov_b32_e32 v32, v2
	v_mov_b32_e32 v33, v2
	v_mov_b32_e32 v42, v2
	v_mov_b32_e32 v43, v2
	v_mov_b32_e32 v44, v2
	v_mov_b32_e32 v45, v2
	v_mov_b32_e32 v46, v2
	v_mov_b32_e32 v47, v2
	v_mov_b32_e32 v48, v2
	v_mov_b32_e32 v49, v2
	v_mov_b32_e32 v58, v2
	v_mov_b32_e32 v59, v2
	v_mov_b32_e32 v60, v2
	v_mov_b32_e32 v61, v2
	v_mov_b32_e32 v62, v2
	v_mov_b32_e32 v63, v2
	v_mov_b32_e32 v64, v2
	v_mov_b32_e32 v65, v2
	v_mov_b32_e32 v66, v2
	v_mov_b32_e32 v67, v2
	v_mov_b32_e32 v68, v2
	v_mov_b32_e32 v69, v2
	v_mov_b32_e32 v70, v2
	v_mov_b32_e32 v71, v2
	v_mov_b32_e32 v72, v2
	v_mov_b32_e32 v73, v2
	v_mov_b32_e32 v82, v2
	v_mov_b32_e32 v83, v2
	v_mov_b32_e32 v84, v2
	v_mov_b32_e32 v85, v2
	v_mov_b32_e32 v86, v2
	v_mov_b32_e32 v87, v2
	v_mov_b32_e32 v88, v2
	v_mov_b32_e32 v89, v2
	v_mov_b32_e32 v98, v2
	v_mov_b32_e32 v99, v2
	v_mov_b32_e32 v100, v2
	v_mov_b32_e32 v101, v2
	v_mov_b32_e32 v102, v2
	v_mov_b32_e32 v103, v2
	v_mov_b32_e32 v104, v2
	v_mov_b32_e32 v105, v2
	v_mov_b32_e32 v114, v2
	v_mov_b32_e32 v115, v2
	v_mov_b32_e32 v116, v2
	v_mov_b32_e32 v117, v2
	v_mov_b32_e32 v118, v2
	v_mov_b32_e32 v119, v2
	v_mov_b32_e32 v120, v2
	v_mov_b32_e32 v121, v2
	v_mov_b32_e32 v74, v2
	v_mov_b32_e32 v75, v2
	v_mov_b32_e32 v76, v2
	v_mov_b32_e32 v77, v2
	v_mov_b32_e32 v78, v2
	v_mov_b32_e32 v79, v2
	v_mov_b32_e32 v80, v2
	v_mov_b32_e32 v81, v2
	v_mov_b32_e32 v90, v2
	v_mov_b32_e32 v91, v2
	v_mov_b32_e32 v92, v2
	v_mov_b32_e32 v93, v2
	v_mov_b32_e32 v94, v2
	v_mov_b32_e32 v95, v2
	v_mov_b32_e32 v96, v2
	v_mov_b32_e32 v97, v2
	v_mov_b32_e32 v106, v2
	v_mov_b32_e32 v107, v2
	v_mov_b32_e32 v108, v2
	v_mov_b32_e32 v109, v2
	v_mov_b32_e32 v110, v2
	v_mov_b32_e32 v111, v2
	v_mov_b32_e32 v112, v2
	v_mov_b32_e32 v113, v2
	v_mov_b32_e32 v122, v2
	v_mov_b32_e32 v123, v2
	v_mov_b32_e32 v124, v2
	v_mov_b32_e32 v125, v2
	v_mov_b32_e32 v126, v2
	v_mov_b32_e32 v127, v2
	v_mov_b32_e32 v128, v2
	v_mov_b32_e32 v129, v2
	.p2alignl 8, 3212836864

.LBB0_411:
	s_ashr_i32 s27, s26, 31
	s_ashr_i32 s29, s28, 31
	s_lshl_b64 s[0:1], s[26:27], 21
	s_lshl_b64 s[14:15], s[28:29], 21
	s_add_u32 s34, s10, s0
	s_addc_u32 s35, s11, s1
	v_readlane_b32 s0, v254, 39
	v_readlane_b32 s1, v254, 40
	s_add_u32 s36, s0, s14
	s_addc_u32 s37, s1, s15
	s_and_b64 s[0:1], s[30:31], exec
	s_cselect_b32 s0, s35, s41
	s_cselect_b32 s1, s34, s40
	s_cselect_b32 s7, s37, s43
	s_cselect_b32 s14, s36, s42
	s_add_u32 s40, s40, 0x100080
	s_addc_u32 s41, s41, 0
	s_add_u32 s15, s42, 0x100
	v_mov_b32_e32 v2, 0
	s_addc_u32 s27, s43, 0
	s_mov_b32 s29, -2
	v_mov_b32_e32 v3, v2
	v_mov_b32_e32 v4, v2
	v_mov_b32_e32 v5, v2
	v_mov_b32_e32 v6, v2
	v_mov_b32_e32 v7, v2
	v_mov_b32_e32 v8, v2
	v_mov_b32_e32 v9, v2
	v_mov_b32_e32 v10, v2
	v_mov_b32_e32 v11, v2
	v_mov_b32_e32 v12, v2
	v_mov_b32_e32 v13, v2
	v_mov_b32_e32 v18, v2
	v_mov_b32_e32 v19, v2
	v_mov_b32_e32 v20, v2
	v_mov_b32_e32 v21, v2
	v_mov_b32_e32 v26, v2
	v_mov_b32_e32 v27, v2
	v_mov_b32_e32 v28, v2
	v_mov_b32_e32 v29, v2
	v_mov_b32_e32 v34, v2
	v_mov_b32_e32 v35, v2
	v_mov_b32_e32 v36, v2
	v_mov_b32_e32 v37, v2
	v_mov_b32_e32 v42, v2
	v_mov_b32_e32 v43, v2
	v_mov_b32_e32 v44, v2
	v_mov_b32_e32 v45, v2
	v_mov_b32_e32 v50, v2
	v_mov_b32_e32 v51, v2
	v_mov_b32_e32 v52, v2
	v_mov_b32_e32 v53, v2
	v_mov_b32_e32 v14, v2
	v_mov_b32_e32 v15, v2
	v_mov_b32_e32 v16, v2
	v_mov_b32_e32 v17, v2
	v_mov_b32_e32 v22, v2
	v_mov_b32_e32 v23, v2
	v_mov_b32_e32 v24, v2
	v_mov_b32_e32 v25, v2
	v_mov_b32_e32 v30, v2
	v_mov_b32_e32 v31, v2
	v_mov_b32_e32 v32, v2
	v_mov_b32_e32 v33, v2
	v_mov_b32_e32 v38, v2
	v_mov_b32_e32 v39, v2
	v_mov_b32_e32 v40, v2
	v_mov_b32_e32 v41, v2
	v_mov_b32_e32 v46, v2
	v_mov_b32_e32 v47, v2
	v_mov_b32_e32 v48, v2
	v_mov_b32_e32 v49, v2
	v_mov_b32_e32 v54, v2
	v_mov_b32_e32 v55, v2
	v_mov_b32_e32 v56, v2
	v_mov_b32_e32 v57, v2
	v_mov_b32_e32 v58, v2
	v_mov_b32_e32 v59, v2
	v_mov_b32_e32 v60, v2
	v_mov_b32_e32 v61, v2
	v_mov_b32_e32 v62, v2
	v_mov_b32_e32 v63, v2
	v_mov_b32_e32 v64, v2
	v_mov_b32_e32 v65, v2
	v_mov_b32_e32 v66, v2
	v_mov_b32_e32 v67, v2
	v_mov_b32_e32 v68, v2
	v_mov_b32_e32 v69, v2
	v_mov_b32_e32 v70, v2
	v_mov_b32_e32 v71, v2
	v_mov_b32_e32 v72, v2
	v_mov_b32_e32 v73, v2
	v_mov_b32_e32 v74, v2
	v_mov_b32_e32 v75, v2
	v_mov_b32_e32 v76, v2
	v_mov_b32_e32 v77, v2
	v_mov_b32_e32 v82, v2
	v_mov_b32_e32 v83, v2
	v_mov_b32_e32 v84, v2
	v_mov_b32_e32 v85, v2
	v_mov_b32_e32 v90, v2
	v_mov_b32_e32 v91, v2
	v_mov_b32_e32 v92, v2
	v_mov_b32_e32 v93, v2
	v_mov_b32_e32 v98, v2
	v_mov_b32_e32 v99, v2
	v_mov_b32_e32 v100, v2
	v_mov_b32_e32 v101, v2
	v_mov_b32_e32 v106, v2
	v_mov_b32_e32 v107, v2
	v_mov_b32_e32 v108, v2
	v_mov_b32_e32 v109, v2
	v_mov_b32_e32 v114, v2
	v_mov_b32_e32 v115, v2
	v_mov_b32_e32 v116, v2
	v_mov_b32_e32 v117, v2
	v_mov_b32_e32 v78, v2
	v_mov_b32_e32 v79, v2
	v_mov_b32_e32 v80, v2
	v_mov_b32_e32 v81, v2
	v_mov_b32_e32 v86, v2
	v_mov_b32_e32 v87, v2
	v_mov_b32_e32 v88, v2
	v_mov_b32_e32 v89, v2
	v_mov_b32_e32 v94, v2
	v_mov_b32_e32 v95, v2
	v_mov_b32_e32 v96, v2
	v_mov_b32_e32 v97, v2
	v_mov_b32_e32 v102, v2
	v_mov_b32_e32 v103, v2
	v_mov_b32_e32 v104, v2
	v_mov_b32_e32 v105, v2
	v_mov_b32_e32 v110, v2
	v_mov_b32_e32 v111, v2
	v_mov_b32_e32 v112, v2
	v_mov_b32_e32 v113, v2
	v_mov_b32_e32 v118, v2
	v_mov_b32_e32 v119, v2
	v_mov_b32_e32 v120, v2
	v_mov_b32_e32 v121, v2
	v_mov_b32_e32 v122, v2
	v_mov_b32_e32 v123, v2
	v_mov_b32_e32 v124, v2
	v_mov_b32_e32 v125, v2
	v_mov_b32_e32 v126, v2
	v_mov_b32_e32 v127, v2
	v_mov_b32_e32 v128, v2
	v_mov_b32_e32 v129, v2
	.p2alignl 8, 3212836864

.LBB0_513:
	s_add_u32 s26, s26, 0x100080
	s_addc_u32 s27, s27, 0
	s_add_u32 s23, s28, 0x100
	v_mov_b32_e32 v2, 0
	s_addc_u32 s49, s29, 0
	s_mov_b32 s50, -2
	v_mov_b32_e32 v3, v2
	v_mov_b32_e32 v4, v2
	v_mov_b32_e32 v5, v2
	v_mov_b32_e32 v6, v2
	v_mov_b32_e32 v7, v2
	v_mov_b32_e32 v8, v2
	v_mov_b32_e32 v9, v2
	v_mov_b32_e32 v10, v2
	v_mov_b32_e32 v11, v2
	v_mov_b32_e32 v12, v2
	v_mov_b32_e32 v13, v2
	v_mov_b32_e32 v18, v2
	v_mov_b32_e32 v19, v2
	v_mov_b32_e32 v20, v2
	v_mov_b32_e32 v21, v2
	v_mov_b32_e32 v26, v2
	v_mov_b32_e32 v27, v2
	v_mov_b32_e32 v28, v2
	v_mov_b32_e32 v29, v2
	v_mov_b32_e32 v34, v2
	v_mov_b32_e32 v35, v2
	v_mov_b32_e32 v36, v2
	v_mov_b32_e32 v37, v2
	v_mov_b32_e32 v42, v2
	v_mov_b32_e32 v43, v2
	v_mov_b32_e32 v44, v2
	v_mov_b32_e32 v45, v2
	v_mov_b32_e32 v50, v2
	v_mov_b32_e32 v51, v2
	v_mov_b32_e32 v52, v2
	v_mov_b32_e32 v53, v2
	v_mov_b32_e32 v14, v2
	v_mov_b32_e32 v15, v2
	v_mov_b32_e32 v16, v2
	v_mov_b32_e32 v17, v2
	v_mov_b32_e32 v22, v2
	v_mov_b32_e32 v23, v2
	v_mov_b32_e32 v24, v2
	v_mov_b32_e32 v25, v2
	v_mov_b32_e32 v30, v2
	v_mov_b32_e32 v31, v2
	v_mov_b32_e32 v32, v2
	v_mov_b32_e32 v33, v2
	v_mov_b32_e32 v38, v2
	v_mov_b32_e32 v39, v2
	v_mov_b32_e32 v40, v2
	v_mov_b32_e32 v41, v2
	v_mov_b32_e32 v46, v2
	v_mov_b32_e32 v47, v2
	v_mov_b32_e32 v48, v2
	v_mov_b32_e32 v49, v2
	v_mov_b32_e32 v54, v2
	v_mov_b32_e32 v55, v2
	v_mov_b32_e32 v56, v2
	v_mov_b32_e32 v57, v2
	v_mov_b32_e32 v58, v2
	v_mov_b32_e32 v59, v2
	v_mov_b32_e32 v60, v2
	v_mov_b32_e32 v61, v2
	v_mov_b32_e32 v62, v2
	v_mov_b32_e32 v63, v2
	v_mov_b32_e32 v64, v2
	v_mov_b32_e32 v65, v2
	v_mov_b32_e32 v66, v2
	v_mov_b32_e32 v67, v2
	v_mov_b32_e32 v68, v2
	v_mov_b32_e32 v69, v2
	v_mov_b32_e32 v70, v2
	v_mov_b32_e32 v71, v2
	v_mov_b32_e32 v72, v2
	v_mov_b32_e32 v73, v2
	v_mov_b32_e32 v78, v2
	v_mov_b32_e32 v79, v2
	v_mov_b32_e32 v80, v2
	v_mov_b32_e32 v81, v2
	v_mov_b32_e32 v86, v2
	v_mov_b32_e32 v87, v2
	v_mov_b32_e32 v88, v2
	v_mov_b32_e32 v89, v2
	v_mov_b32_e32 v90, v2
	v_mov_b32_e32 v91, v2
	v_mov_b32_e32 v92, v2
	v_mov_b32_e32 v93, v2
	v_mov_b32_e32 v98, v2
	v_mov_b32_e32 v99, v2
	v_mov_b32_e32 v100, v2
	v_mov_b32_e32 v101, v2
	v_mov_b32_e32 v106, v2
	v_mov_b32_e32 v107, v2
	v_mov_b32_e32 v108, v2
	v_mov_b32_e32 v109, v2
	v_mov_b32_e32 v114, v2
	v_mov_b32_e32 v115, v2
	v_mov_b32_e32 v116, v2
	v_mov_b32_e32 v117, v2
	v_mov_b32_e32 v74, v2
	v_mov_b32_e32 v75, v2
	v_mov_b32_e32 v76, v2
	v_mov_b32_e32 v77, v2
	v_mov_b32_e32 v82, v2
	v_mov_b32_e32 v83, v2
	v_mov_b32_e32 v84, v2
	v_mov_b32_e32 v85, v2
	v_mov_b32_e32 v94, v2
	v_mov_b32_e32 v95, v2
	v_mov_b32_e32 v96, v2
	v_mov_b32_e32 v97, v2
	v_mov_b32_e32 v102, v2
	v_mov_b32_e32 v103, v2
	v_mov_b32_e32 v104, v2
	v_mov_b32_e32 v105, v2
	v_mov_b32_e32 v110, v2
	v_mov_b32_e32 v111, v2
	v_mov_b32_e32 v112, v2
	v_mov_b32_e32 v113, v2
	v_mov_b32_e32 v118, v2
	v_mov_b32_e32 v119, v2
	v_mov_b32_e32 v120, v2
	v_mov_b32_e32 v121, v2
	v_mov_b32_e32 v122, v2
	v_mov_b32_e32 v123, v2
	v_mov_b32_e32 v124, v2
	v_mov_b32_e32 v125, v2
	v_mov_b32_e32 v126, v2
	v_mov_b32_e32 v127, v2
	v_mov_b32_e32 v128, v2
	v_mov_b32_e32 v129, v2
	.p2alignl 8, 3212836864

.LBB0_733:
	s_add_u32 s77, s36, 0x100
	s_addc_u32 s78, s37, 0
	s_lshl_b32 s36, s2, 1
	s_or_b32 s0, s36, 1
	s_ashr_i32 s1, s0, 31
	s_lshl_b64 s[0:1], s[0:1], 20
	v_readlane_b32 s14, v254, 41
	v_readlane_b32 s15, v254, 42
	s_add_u32 s0, s14, s0
	v_mov_b32_e32 v2, 0
	s_addc_u32 s1, s15, s1
	v_lshl_add_u64 v[162:163], s[30:31], 0, v[210:211]
	v_lshl_add_u64 v[164:165], s[30:31], 0, v[214:215]
	s_mov_b32 s3, -2
	s_mov_b64 s[34:35], 0
	v_mov_b32_e32 v3, v2
	v_mov_b32_e32 v4, v2
	v_mov_b32_e32 v5, v2
	v_mov_b32_e32 v6, v2
	v_mov_b32_e32 v7, v2
	v_mov_b32_e32 v8, v2
	v_mov_b32_e32 v9, v2
	v_mov_b32_e32 v18, v2
	v_mov_b32_e32 v19, v2
	v_mov_b32_e32 v20, v2
	v_mov_b32_e32 v21, v2
	v_mov_b32_e32 v22, v2
	v_mov_b32_e32 v23, v2
	v_mov_b32_e32 v24, v2
	v_mov_b32_e32 v25, v2
	v_mov_b32_e32 v34, v2
	v_mov_b32_e32 v35, v2
	v_mov_b32_e32 v36, v2
	v_mov_b32_e32 v37, v2
	v_mov_b32_e32 v38, v2
	v_mov_b32_e32 v39, v2
	v_mov_b32_e32 v40, v2
	v_mov_b32_e32 v41, v2
	v_mov_b32_e32 v66, v2
	v_mov_b32_e32 v67, v2
	v_mov_b32_e32 v68, v2
	v_mov_b32_e32 v69, v2
	v_mov_b32_e32 v70, v2
	v_mov_b32_e32 v71, v2
	v_mov_b32_e32 v72, v2
	v_mov_b32_e32 v73, v2
	v_mov_b32_e32 v10, v2
	v_mov_b32_e32 v11, v2
	v_mov_b32_e32 v12, v2
	v_mov_b32_e32 v13, v2
	v_mov_b32_e32 v14, v2
	v_mov_b32_e32 v15, v2
	v_mov_b32_e32 v16, v2
	v_mov_b32_e32 v17, v2
	v_mov_b32_e32 v26, v2
	v_mov_b32_e32 v27, v2
	v_mov_b32_e32 v28, v2
	v_mov_b32_e32 v29, v2
	v_mov_b32_e32 v30, v2
	v_mov_b32_e32 v31, v2
	v_mov_b32_e32 v32, v2
	v_mov_b32_e32 v33, v2
	v_mov_b32_e32 v42, v2
	v_mov_b32_e32 v43, v2
	v_mov_b32_e32 v44, v2
	v_mov_b32_e32 v45, v2
	v_mov_b32_e32 v46, v2
	v_mov_b32_e32 v47, v2
	v_mov_b32_e32 v48, v2
	v_mov_b32_e32 v49, v2
	v_mov_b32_e32 v74, v2
	v_mov_b32_e32 v75, v2
	v_mov_b32_e32 v76, v2
	v_mov_b32_e32 v77, v2
	v_mov_b32_e32 v78, v2
	v_mov_b32_e32 v79, v2
	v_mov_b32_e32 v80, v2
	v_mov_b32_e32 v81, v2
	v_mov_b32_e32 v82, v2
	v_mov_b32_e32 v83, v2
	v_mov_b32_e32 v84, v2
	v_mov_b32_e32 v85, v2
	v_mov_b32_e32 v86, v2
	v_mov_b32_e32 v87, v2
	v_mov_b32_e32 v88, v2
	v_mov_b32_e32 v89, v2
	v_mov_b32_e32 v98, v2
	v_mov_b32_e32 v99, v2
	v_mov_b32_e32 v100, v2
	v_mov_b32_e32 v101, v2
	v_mov_b32_e32 v102, v2
	v_mov_b32_e32 v103, v2
	v_mov_b32_e32 v104, v2
	v_mov_b32_e32 v105, v2
	v_mov_b32_e32 v114, v2
	v_mov_b32_e32 v115, v2
	v_mov_b32_e32 v116, v2
	v_mov_b32_e32 v117, v2
	v_mov_b32_e32 v118, v2
	v_mov_b32_e32 v119, v2
	v_mov_b32_e32 v120, v2
	v_mov_b32_e32 v121, v2
	v_mov_b32_e32 v130, v2
	v_mov_b32_e32 v131, v2
	v_mov_b32_e32 v132, v2
	v_mov_b32_e32 v133, v2
	v_mov_b32_e32 v134, v2
	v_mov_b32_e32 v135, v2
	v_mov_b32_e32 v136, v2
	v_mov_b32_e32 v137, v2
	v_mov_b32_e32 v90, v2
	v_mov_b32_e32 v91, v2
	v_mov_b32_e32 v92, v2
	v_mov_b32_e32 v93, v2
	v_mov_b32_e32 v94, v2
	v_mov_b32_e32 v95, v2
	v_mov_b32_e32 v96, v2
	v_mov_b32_e32 v97, v2
	v_mov_b32_e32 v106, v2
	v_mov_b32_e32 v107, v2
	v_mov_b32_e32 v108, v2
	v_mov_b32_e32 v109, v2
	v_mov_b32_e32 v110, v2
	v_mov_b32_e32 v111, v2
	v_mov_b32_e32 v112, v2
	v_mov_b32_e32 v113, v2
	v_mov_b32_e32 v122, v2
	v_mov_b32_e32 v123, v2
	v_mov_b32_e32 v124, v2
	v_mov_b32_e32 v125, v2
	v_mov_b32_e32 v126, v2
	v_mov_b32_e32 v127, v2
	v_mov_b32_e32 v128, v2
	v_mov_b32_e32 v129, v2
	v_mov_b32_e32 v138, v2
	v_mov_b32_e32 v139, v2
	v_mov_b32_e32 v140, v2
	v_mov_b32_e32 v141, v2
	v_mov_b32_e32 v142, v2
	v_mov_b32_e32 v143, v2
	v_mov_b32_e32 v144, v2
	v_mov_b32_e32 v145, v2
	.p2alignl 8, 3212836864

.LBB0_739:
	s_ashr_i32 s29, s28, 31
	s_ashr_i32 s3, s2, 31
	s_lshl_b64 s[34:35], s[28:29], 20
	s_lshl_b64 s[2:3], s[2:3], 20
	v_readlane_b32 s0, v253, 4
	v_readlane_b32 s1, v253, 5
	s_add_u32 s0, s0, s34
	s_addc_u32 s1, s1, s35
	v_readlane_b32 s14, v254, 43
	v_readlane_b32 s15, v254, 44
	s_add_u32 s14, s14, s2
	s_addc_u32 s15, s15, s3
	s_add_u32 s38, s30, 0x80080
	s_addc_u32 s39, s31, 0
	s_ashr_i32 s37, s36, 31
	s_lshl_b64 s[36:37], s[36:37], 20
	s_add_u32 s25, s54, s36
	v_mov_b32_e32 v2, 0
	s_addc_u32 s29, s55, s37
	s_mov_b32 s33, -2
	v_mov_b32_e32 v3, v2
	v_mov_b32_e32 v4, v2
	v_mov_b32_e32 v5, v2
	v_mov_b32_e32 v6, v2
	v_mov_b32_e32 v7, v2
	v_mov_b32_e32 v8, v2
	v_mov_b32_e32 v9, v2
	v_mov_b32_e32 v18, v2
	v_mov_b32_e32 v19, v2
	v_mov_b32_e32 v20, v2
	v_mov_b32_e32 v21, v2
	v_mov_b32_e32 v22, v2
	v_mov_b32_e32 v23, v2
	v_mov_b32_e32 v24, v2
	v_mov_b32_e32 v25, v2
	v_mov_b32_e32 v34, v2
	v_mov_b32_e32 v35, v2
	v_mov_b32_e32 v36, v2
	v_mov_b32_e32 v37, v2
	v_mov_b32_e32 v38, v2
	v_mov_b32_e32 v39, v2
	v_mov_b32_e32 v40, v2
	v_mov_b32_e32 v41, v2
	v_mov_b32_e32 v66, v2
	v_mov_b32_e32 v67, v2
	v_mov_b32_e32 v68, v2
	v_mov_b32_e32 v69, v2
	v_mov_b32_e32 v70, v2
	v_mov_b32_e32 v71, v2
	v_mov_b32_e32 v72, v2
	v_mov_b32_e32 v73, v2
	v_mov_b32_e32 v10, v2
	v_mov_b32_e32 v11, v2
	v_mov_b32_e32 v12, v2
	v_mov_b32_e32 v13, v2
	v_mov_b32_e32 v14, v2
	v_mov_b32_e32 v15, v2
	v_mov_b32_e32 v16, v2
	v_mov_b32_e32 v17, v2
	v_mov_b32_e32 v26, v2
	v_mov_b32_e32 v27, v2
	v_mov_b32_e32 v28, v2
	v_mov_b32_e32 v29, v2
	v_mov_b32_e32 v30, v2
	v_mov_b32_e32 v31, v2
	v_mov_b32_e32 v32, v2
	v_mov_b32_e32 v33, v2
	v_mov_b32_e32 v42, v2
	v_mov_b32_e32 v43, v2
	v_mov_b32_e32 v44, v2
	v_mov_b32_e32 v45, v2
	v_mov_b32_e32 v46, v2
	v_mov_b32_e32 v47, v2
	v_mov_b32_e32 v48, v2
	v_mov_b32_e32 v49, v2
	v_mov_b32_e32 v74, v2
	v_mov_b32_e32 v75, v2
	v_mov_b32_e32 v76, v2
	v_mov_b32_e32 v77, v2
	v_mov_b32_e32 v78, v2
	v_mov_b32_e32 v79, v2
	v_mov_b32_e32 v80, v2
	v_mov_b32_e32 v81, v2
	v_mov_b32_e32 v82, v2
	v_mov_b32_e32 v83, v2
	v_mov_b32_e32 v84, v2
	v_mov_b32_e32 v85, v2
	v_mov_b32_e32 v86, v2
	v_mov_b32_e32 v87, v2
	v_mov_b32_e32 v88, v2
	v_mov_b32_e32 v89, v2
	v_mov_b32_e32 v98, v2
	v_mov_b32_e32 v99, v2
	v_mov_b32_e32 v100, v2
	v_mov_b32_e32 v101, v2
	v_mov_b32_e32 v102, v2
	v_mov_b32_e32 v103, v2
	v_mov_b32_e32 v104, v2
	v_mov_b32_e32 v105, v2
	v_mov_b32_e32 v114, v2
	v_mov_b32_e32 v115, v2
	v_mov_b32_e32 v116, v2
	v_mov_b32_e32 v117, v2
	v_mov_b32_e32 v118, v2
	v_mov_b32_e32 v119, v2
	v_mov_b32_e32 v120, v2
	v_mov_b32_e32 v121, v2
	v_mov_b32_e32 v130, v2
	v_mov_b32_e32 v131, v2
	v_mov_b32_e32 v132, v2
	v_mov_b32_e32 v133, v2
	v_mov_b32_e32 v134, v2
	v_mov_b32_e32 v135, v2
	v_mov_b32_e32 v136, v2
	v_mov_b32_e32 v137, v2
	v_mov_b32_e32 v90, v2
	v_mov_b32_e32 v91, v2
	v_mov_b32_e32 v92, v2
	v_mov_b32_e32 v93, v2
	v_mov_b32_e32 v94, v2
	v_mov_b32_e32 v95, v2
	v_mov_b32_e32 v96, v2
	v_mov_b32_e32 v97, v2
	v_mov_b32_e32 v106, v2
	v_mov_b32_e32 v107, v2
	v_mov_b32_e32 v108, v2
	v_mov_b32_e32 v109, v2
	v_mov_b32_e32 v110, v2
	v_mov_b32_e32 v111, v2
	v_mov_b32_e32 v112, v2
	v_mov_b32_e32 v113, v2
	v_mov_b32_e32 v122, v2
	v_mov_b32_e32 v123, v2
	v_mov_b32_e32 v124, v2
	v_mov_b32_e32 v125, v2
	v_mov_b32_e32 v126, v2
	v_mov_b32_e32 v127, v2
	v_mov_b32_e32 v128, v2
	v_mov_b32_e32 v129, v2
	v_mov_b32_e32 v138, v2
	v_mov_b32_e32 v139, v2
	v_mov_b32_e32 v140, v2
	v_mov_b32_e32 v141, v2
	v_mov_b32_e32 v142, v2
	v_mov_b32_e32 v143, v2
	v_mov_b32_e32 v144, v2
	v_mov_b32_e32 v145, v2
	.p2alignl 8, 3212836864

.LBB0_745:
	v_readlane_b32 s0, v254, 39
	v_readlane_b32 s1, v254, 40
	s_add_u32 s0, s0, s34
	s_addc_u32 s1, s1, s35
	v_readlane_b32 s14, v253, 10
	v_readlane_b32 s15, v253, 11
	s_add_u32 s14, s14, s2
	v_readlane_b32 s88, v253, 29
	s_addc_u32 s15, s15, s3
	v_readlane_b32 s94, v253, 35
	v_readlane_b32 s95, v253, 36
	s_add_u32 s29, s94, s34
	s_addc_u32 s33, s95, s35
	s_add_u32 s25, s56, s2
	v_mov_b32_e32 v2, 0
	v_readlane_b32 s89, v253, 30
	v_readlane_b32 s90, v253, 31
	v_readlane_b32 s91, v253, 32
	v_readlane_b32 s92, v253, 33
	v_readlane_b32 s93, v253, 34
	v_lshl_add_u64 v[162:163], v[216:217], 0, s[34:35]
	v_lshl_add_u64 v[164:165], v[218:219], 0, s[34:35]
	s_addc_u32 s79, s57, s3
	s_mov_b32 s80, -2
	s_mov_b64 s[36:37], 0
	v_mov_b32_e32 v3, v2
	v_mov_b32_e32 v4, v2
	v_mov_b32_e32 v5, v2
	v_mov_b32_e32 v6, v2
	v_mov_b32_e32 v7, v2
	v_mov_b32_e32 v8, v2
	v_mov_b32_e32 v9, v2
	v_mov_b32_e32 v18, v2
	v_mov_b32_e32 v19, v2
	v_mov_b32_e32 v20, v2
	v_mov_b32_e32 v21, v2
	v_mov_b32_e32 v22, v2
	v_mov_b32_e32 v23, v2
	v_mov_b32_e32 v24, v2
	v_mov_b32_e32 v25, v2
	v_mov_b32_e32 v66, v2
	v_mov_b32_e32 v67, v2
	v_mov_b32_e32 v68, v2
	v_mov_b32_e32 v69, v2
	v_mov_b32_e32 v78, v2
	v_mov_b32_e32 v79, v2
	v_mov_b32_e32 v80, v2
	v_mov_b32_e32 v81, v2
	v_mov_b32_e32 v114, v2
	v_mov_b32_e32 v115, v2
	v_mov_b32_e32 v116, v2
	v_mov_b32_e32 v117, v2
	v_mov_b32_e32 v122, v2
	v_mov_b32_e32 v123, v2
	v_mov_b32_e32 v124, v2
	v_mov_b32_e32 v125, v2
	v_mov_b32_e32 v10, v2
	v_mov_b32_e32 v11, v2
	v_mov_b32_e32 v12, v2
	v_mov_b32_e32 v13, v2
	v_mov_b32_e32 v14, v2
	v_mov_b32_e32 v15, v2
	v_mov_b32_e32 v16, v2
	v_mov_b32_e32 v17, v2
	v_mov_b32_e32 v50, v2
	v_mov_b32_e32 v51, v2
	v_mov_b32_e32 v52, v2
	v_mov_b32_e32 v53, v2
	v_mov_b32_e32 v62, v2
	v_mov_b32_e32 v63, v2
	v_mov_b32_e32 v64, v2
	v_mov_b32_e32 v65, v2
	v_mov_b32_e32 v118, v2
	v_mov_b32_e32 v119, v2
	v_mov_b32_e32 v120, v2
	v_mov_b32_e32 v121, v2
	v_mov_b32_e32 v126, v2
	v_mov_b32_e32 v127, v2
	v_mov_b32_e32 v128, v2
	v_mov_b32_e32 v129, v2
	v_mov_b32_e32 v106, v2
	v_mov_b32_e32 v107, v2
	v_mov_b32_e32 v108, v2
	v_mov_b32_e32 v109, v2
	v_mov_b32_e32 v110, v2
	v_mov_b32_e32 v111, v2
	v_mov_b32_e32 v112, v2
	v_mov_b32_e32 v113, v2
	v_mov_b32_e32 v98, v2
	v_mov_b32_e32 v99, v2
	v_mov_b32_e32 v100, v2
	v_mov_b32_e32 v101, v2
	v_mov_b32_e32 v102, v2
	v_mov_b32_e32 v103, v2
	v_mov_b32_e32 v104, v2
	v_mov_b32_e32 v105, v2
	v_mov_b32_e32 v82, v2
	v_mov_b32_e32 v83, v2
	v_mov_b32_e32 v84, v2
	v_mov_b32_e32 v85, v2
	v_mov_b32_e32 v86, v2
	v_mov_b32_e32 v87, v2
	v_mov_b32_e32 v88, v2
	v_mov_b32_e32 v89, v2
	v_mov_b32_e32 v54, v2
	v_mov_b32_e32 v55, v2
	v_mov_b32_e32 v56, v2
	v_mov_b32_e32 v57, v2
	v_mov_b32_e32 v58, v2
	v_mov_b32_e32 v59, v2
	v_mov_b32_e32 v60, v2
	v_mov_b32_e32 v61, v2
	v_mov_b32_e32 v34, v2
	v_mov_b32_e32 v35, v2
	v_mov_b32_e32 v36, v2
	v_mov_b32_e32 v37, v2
	v_mov_b32_e32 v38, v2
	v_mov_b32_e32 v39, v2
	v_mov_b32_e32 v40, v2
	v_mov_b32_e32 v41, v2
	v_mov_b32_e32 v90, v2
	v_mov_b32_e32 v91, v2
	v_mov_b32_e32 v92, v2
	v_mov_b32_e32 v93, v2
	v_mov_b32_e32 v94, v2
	v_mov_b32_e32 v95, v2
	v_mov_b32_e32 v96, v2
	v_mov_b32_e32 v97, v2
	v_mov_b32_e32 v70, v2
	v_mov_b32_e32 v71, v2
	v_mov_b32_e32 v72, v2
	v_mov_b32_e32 v73, v2
	v_mov_b32_e32 v74, v2
	v_mov_b32_e32 v75, v2
	v_mov_b32_e32 v76, v2
	v_mov_b32_e32 v77, v2
	v_mov_b32_e32 v42, v2
	v_mov_b32_e32 v43, v2
	v_mov_b32_e32 v44, v2
	v_mov_b32_e32 v45, v2
	v_mov_b32_e32 v46, v2
	v_mov_b32_e32 v47, v2
	v_mov_b32_e32 v48, v2
	v_mov_b32_e32 v49, v2
	v_mov_b32_e32 v26, v2
	v_mov_b32_e32 v27, v2
	v_mov_b32_e32 v28, v2
	v_mov_b32_e32 v29, v2
	v_mov_b32_e32 v30, v2
	v_mov_b32_e32 v31, v2
	v_mov_b32_e32 v32, v2
	v_mov_b32_e32 v33, v2
	.p2alignl 8, 3212836864

.LBB0_751:
	v_cvt_f32_i32_e32 v31, v31
	v_cvt_f32_i32_e32 v30, v30
	v_cvt_f32_i32_e32 v33, v33
	v_cvt_f32_i32_e32 v32, v32
	v_cvt_f32_i32_e32 v27, v27
	v_cvt_f32_i32_e32 v29, v29
	v_cvt_f32_i32_e32 v28, v28
	v_cvt_f32_i32_e32 v26, v26
	v_cvt_f32_i32_e32 v39, v39
	v_cvt_f32_i32_e32 v38, v38
	v_cvt_f32_i32_e32 v41, v41
	v_cvt_f32_i32_e32 v40, v40
	v_cvt_f32_i32_e32 v35, v35
	v_cvt_f32_i32_e32 v37, v37
	v_cvt_f32_i32_e32 v36, v36
	v_cvt_f32_i32_e32 v34, v34
	v_cvt_f32_i32_e32 v47, v47
	v_cvt_f32_i32_e32 v46, v46
	v_cvt_f32_i32_e32 v49, v49
	v_cvt_f32_i32_e32 v48, v48
	v_cvt_f32_i32_e32 v43, v43
	v_cvt_f32_i32_e32 v45, v45
	v_cvt_f32_i32_e32 v44, v44
	v_cvt_f32_i32_e32 v42, v42
	v_cvt_f32_i32_e32 v59, v59
	v_cvt_f32_i32_e32 v58, v58
	v_cvt_f32_i32_e32 v61, v61
	v_cvt_f32_i32_e32 v60, v60
	v_cvt_f32_i32_e32 v55, v55
	v_cvt_f32_i32_e32 v57, v57
	v_cvt_f32_i32_e32 v56, v56
	v_cvt_f32_i32_e32 v54, v54
	v_pk_mul_f32 v[32:33], v[32:33], s[22:23] op_sel_hi:[1,0]
	v_pk_mul_f32 v[30:31], v[30:31], s[22:23] op_sel_hi:[1,0]
	v_pk_mul_f32 v[238:239], v[28:29], s[22:23] op_sel_hi:[1,0]
	v_pk_mul_f32 v[240:241], v[26:27], s[22:23] op_sel_hi:[1,0]
	s_waitcnt vmcnt(0)
	v_lshlrev_b32_e32 v26, 16, v190
	v_and_b32_e32 v27, 0xffff0000, v190
	v_lshlrev_b32_e32 v28, 16, v191
	v_and_b32_e32 v29, 0xffff0000, v191
	v_cvt_f32_i32_e32 v75, v75
	v_cvt_f32_i32_e32 v74, v74
	v_cvt_f32_i32_e32 v77, v77
	v_cvt_f32_i32_e32 v76, v76
	v_cvt_f32_i32_e32 v71, v71
	v_cvt_f32_i32_e32 v73, v73
	v_cvt_f32_i32_e32 v72, v72
	v_cvt_f32_i32_e32 v70, v70
	v_pk_mul_f32 v[26:27], v[30:31], v[26:27]
	v_pk_mul_f32 v[28:29], v[32:33], v[28:29]
	v_lshlrev_b32_e32 v30, 16, v192
	v_and_b32_e32 v31, 0xffff0000, v192
	v_lshlrev_b32_e32 v32, 16, v193
	v_and_b32_e32 v33, 0xffff0000, v193
	v_pk_mul_f32 v[40:41], v[40:41], s[22:23] op_sel_hi:[1,0]
	v_pk_mul_f32 v[38:39], v[38:39], s[22:23] op_sel_hi:[1,0]
	v_pk_mul_f32 v[190:191], v[36:37], s[22:23] op_sel_hi:[1,0]
	v_pk_mul_f32 v[192:193], v[34:35], s[22:23] op_sel_hi:[1,0]
	v_lshlrev_b32_e32 v34, 16, v186
	v_and_b32_e32 v35, 0xffff0000, v186
	v_lshlrev_b32_e32 v36, 16, v187
	v_and_b32_e32 v37, 0xffff0000, v187
	v_cvt_f32_i32_e32 v87, v87
	v_cvt_f32_i32_e32 v86, v86
	v_cvt_f32_i32_e32 v89, v89
	v_cvt_f32_i32_e32 v88, v88
	v_cvt_f32_i32_e32 v83, v83
	v_cvt_f32_i32_e32 v85, v85
	v_cvt_f32_i32_e32 v84, v84
	v_cvt_f32_i32_e32 v82, v82
	v_pk_mul_f32 v[34:35], v[38:39], v[34:35]
	v_pk_mul_f32 v[36:37], v[40:41], v[36:37]
	v_lshlrev_b32_e32 v38, 16, v188
	v_and_b32_e32 v39, 0xffff0000, v188
	v_lshlrev_b32_e32 v40, 16, v189
	v_and_b32_e32 v41, 0xffff0000, v189
	v_pk_mul_f32 v[48:49], v[48:49], s[22:23] op_sel_hi:[1,0]
	v_pk_mul_f32 v[46:47], v[46:47], s[22:23] op_sel_hi:[1,0]
	v_pk_mul_f32 v[186:187], v[44:45], s[22:23] op_sel_hi:[1,0]
	v_pk_mul_f32 v[188:189], v[42:43], s[22:23] op_sel_hi:[1,0]
	v_lshlrev_b32_e32 v42, 16, v182
	v_and_b32_e32 v43, 0xffff0000, v182
	v_lshlrev_b32_e32 v44, 16, v183
	v_and_b32_e32 v45, 0xffff0000, v183
	v_cvt_f32_i32_e32 v95, v95
	v_cvt_f32_i32_e32 v94, v94
	v_cvt_f32_i32_e32 v97, v97
	v_cvt_f32_i32_e32 v96, v96
	v_cvt_f32_i32_e32 v91, v91
	v_cvt_f32_i32_e32 v93, v93
	v_cvt_f32_i32_e32 v92, v92
	v_cvt_f32_i32_e32 v90, v90
	v_pk_mul_f32 v[42:43], v[46:47], v[42:43]
	v_pk_mul_f32 v[44:45], v[48:49], v[44:45]
	v_lshlrev_b32_e32 v46, 16, v184
	v_and_b32_e32 v47, 0xffff0000, v184
	v_lshlrev_b32_e32 v48, 16, v185
	v_and_b32_e32 v49, 0xffff0000, v185
	v_pk_mul_f32 v[60:61], v[60:61], s[22:23] op_sel_hi:[1,0]
	v_pk_mul_f32 v[58:59], v[58:59], s[22:23] op_sel_hi:[1,0]
	v_pk_mul_f32 v[182:183], v[56:57], s[22:23] op_sel_hi:[1,0]
	v_pk_mul_f32 v[184:185], v[54:55], s[22:23] op_sel_hi:[1,0]
	v_lshlrev_b32_e32 v54, 16, v178
	v_and_b32_e32 v55, 0xffff0000, v178
	v_lshlrev_b32_e32 v56, 16, v179
	v_and_b32_e32 v57, 0xffff0000, v179
	v_cvt_f32_i32_e32 v103, v103
	v_cvt_f32_i32_e32 v102, v102
	v_cvt_f32_i32_e32 v105, v105
	v_cvt_f32_i32_e32 v104, v104
	v_cvt_f32_i32_e32 v99, v99
	v_cvt_f32_i32_e32 v101, v101
	v_cvt_f32_i32_e32 v100, v100
	v_cvt_f32_i32_e32 v98, v98
	v_pk_mul_f32 v[54:55], v[58:59], v[54:55]
	v_pk_mul_f32 v[56:57], v[60:61], v[56:57]
	v_lshlrev_b32_e32 v58, 16, v180
	v_and_b32_e32 v59, 0xffff0000, v180
	v_lshlrev_b32_e32 v60, 16, v181
	v_and_b32_e32 v61, 0xffff0000, v181
	v_pk_mul_f32 v[76:77], v[76:77], s[22:23] op_sel_hi:[1,0]
	v_pk_mul_f32 v[74:75], v[74:75], s[22:23] op_sel_hi:[1,0]
	v_pk_mul_f32 v[178:179], v[72:73], s[22:23] op_sel_hi:[1,0]
	v_pk_mul_f32 v[180:181], v[70:71], s[22:23] op_sel_hi:[1,0]
	v_lshlrev_b32_e32 v70, 16, v174
	v_and_b32_e32 v71, 0xffff0000, v174
	v_lshlrev_b32_e32 v72, 16, v175
	v_and_b32_e32 v73, 0xffff0000, v175
	v_cvt_f32_i32_e32 v111, v111
	v_cvt_f32_i32_e32 v110, v110
	v_cvt_f32_i32_e32 v113, v113
	v_cvt_f32_i32_e32 v112, v112
	v_cvt_f32_i32_e32 v107, v107
	v_cvt_f32_i32_e32 v109, v109
	v_cvt_f32_i32_e32 v108, v108
	v_cvt_f32_i32_e32 v106, v106
	v_pk_mul_f32 v[70:71], v[74:75], v[70:71]
	v_pk_mul_f32 v[72:73], v[76:77], v[72:73]
	v_lshlrev_b32_e32 v74, 16, v176
	v_and_b32_e32 v75, 0xffff0000, v176
	v_lshlrev_b32_e32 v76, 16, v177
	v_and_b32_e32 v77, 0xffff0000, v177
	v_pk_mul_f32 v[88:89], v[88:89], s[22:23] op_sel_hi:[1,0]
	v_pk_mul_f32 v[86:87], v[86:87], s[22:23] op_sel_hi:[1,0]
	v_pk_mul_f32 v[174:175], v[84:85], s[22:23] op_sel_hi:[1,0]
	v_pk_mul_f32 v[176:177], v[82:83], s[22:23] op_sel_hi:[1,0]
	v_lshlrev_b32_e32 v82, 16, v170
	v_and_b32_e32 v83, 0xffff0000, v170
	v_lshlrev_b32_e32 v84, 16, v171
	v_and_b32_e32 v85, 0xffff0000, v171
	v_cvt_f32_i32_e32 v123, v123
	v_cvt_f32_i32_e32 v122, v122
	v_cvt_f32_i32_e32 v125, v125
	v_cvt_f32_i32_e32 v124, v124
	v_cvt_f32_i32_e32 v115, v115
	v_cvt_f32_i32_e32 v117, v117
	v_cvt_f32_i32_e32 v116, v116
	v_cvt_f32_i32_e32 v114, v114
	s_ashr_i32 s25, s24, 31
	v_pk_mul_f32 v[82:83], v[86:87], v[82:83]
	v_pk_mul_f32 v[84:85], v[88:89], v[84:85]
	v_lshlrev_b32_e32 v86, 16, v172
	v_and_b32_e32 v87, 0xffff0000, v172
	v_lshlrev_b32_e32 v88, 16, v173
	v_and_b32_e32 v89, 0xffff0000, v173
	v_pk_mul_f32 v[96:97], v[96:97], s[22:23] op_sel_hi:[1,0]
	v_pk_mul_f32 v[94:95], v[94:95], s[22:23] op_sel_hi:[1,0]
	v_pk_mul_f32 v[170:171], v[92:93], s[22:23] op_sel_hi:[1,0]
	v_pk_mul_f32 v[172:173], v[90:91], s[22:23] op_sel_hi:[1,0]
	v_lshlrev_b32_e32 v90, 16, v166
	v_and_b32_e32 v91, 0xffff0000, v166
	v_lshlrev_b32_e32 v92, 16, v167
	v_and_b32_e32 v93, 0xffff0000, v167
	v_cvt_f32_i32_e32 v127, v127
	v_cvt_f32_i32_e32 v126, v126
	v_cvt_f32_i32_e32 v129, v129
	v_cvt_f32_i32_e32 v128, v128
	v_cvt_f32_i32_e32 v119, v119
	v_cvt_f32_i32_e32 v121, v121
	v_cvt_f32_i32_e32 v120, v120
	v_cvt_f32_i32_e32 v118, v118
	s_lshl_b64 s[0:1], s[24:25], 20
	s_lshl_b32 s14, s65, 1
	v_readlane_b32 s15, v254, 54
	v_pk_mul_f32 v[90:91], v[94:95], v[90:91]
	v_pk_mul_f32 v[92:93], v[96:97], v[92:93]
	v_lshlrev_b32_e32 v94, 16, v168
	v_and_b32_e32 v95, 0xffff0000, v168
	v_lshlrev_b32_e32 v96, 16, v169
	v_and_b32_e32 v97, 0xffff0000, v169
	v_pk_mul_f32 v[104:105], v[104:105], s[22:23] op_sel_hi:[1,0]
	v_pk_mul_f32 v[102:103], v[102:103], s[22:23] op_sel_hi:[1,0]
	v_pk_mul_f32 v[166:167], v[100:101], s[22:23] op_sel_hi:[1,0]
	v_pk_mul_f32 v[168:169], v[98:99], s[22:23] op_sel_hi:[1,0]
	v_lshlrev_b32_e32 v98, 16, v162
	v_and_b32_e32 v99, 0xffff0000, v162
	v_lshlrev_b32_e32 v100, 16, v163
	v_and_b32_e32 v101, 0xffff0000, v163
	v_cvt_f32_i32_e32 v79, v79
	v_cvt_f32_i32_e32 v78, v78
	v_cvt_f32_i32_e32 v81, v81
	v_cvt_f32_i32_e32 v80, v80
	v_cvt_f32_i32_e32 v67, v67
	v_cvt_f32_i32_e32 v69, v69
	v_cvt_f32_i32_e32 v68, v68
	v_cvt_f32_i32_e32 v66, v66
	s_add_u32 s38, s15, s0
	v_readlane_b32 s0, v254, 56
	v_pk_mul_f32 v[98:99], v[102:103], v[98:99]
	v_pk_mul_f32 v[100:101], v[104:105], v[100:101]
	v_lshlrev_b32_e32 v102, 16, v164
	v_and_b32_e32 v103, 0xffff0000, v164
	v_lshlrev_b32_e32 v104, 16, v165
	v_and_b32_e32 v105, 0xffff0000, v165
	v_pk_mul_f32 v[112:113], v[112:113], s[22:23] op_sel_hi:[1,0]
	v_pk_mul_f32 v[110:111], v[110:111], s[22:23] op_sel_hi:[1,0]
	v_pk_mul_f32 v[162:163], v[108:109], s[22:23] op_sel_hi:[1,0]
	v_pk_mul_f32 v[164:165], v[106:107], s[22:23] op_sel_hi:[1,0]
	v_lshlrev_b32_e32 v106, 16, v158
	v_and_b32_e32 v107, 0xffff0000, v158
	v_lshlrev_b32_e32 v108, 16, v159
	v_and_b32_e32 v109, 0xffff0000, v159
	v_cvt_f32_i32_e32 v63, v63
	v_cvt_f32_i32_e32 v62, v62
	v_cvt_f32_i32_e32 v65, v65
	v_cvt_f32_i32_e32 v64, v64
	v_cvt_f32_i32_e32 v51, v51
	v_cvt_f32_i32_e32 v53, v53
	v_cvt_f32_i32_e32 v52, v52
	v_cvt_f32_i32_e32 v50, v50
	s_addc_u32 s39, s0, s1
	v_pk_mul_f32 v[106:107], v[110:111], v[106:107]
	v_pk_mul_f32 v[108:109], v[112:113], v[108:109]
	v_lshlrev_b32_e32 v110, 16, v160
	v_and_b32_e32 v111, 0xffff0000, v160
	v_lshlrev_b32_e32 v112, 16, v161
	v_and_b32_e32 v113, 0xffff0000, v161
	v_pk_mul_f32 v[124:125], v[124:125], s[22:23] op_sel_hi:[1,0]
	v_pk_mul_f32 v[122:123], v[122:123], s[22:23] op_sel_hi:[1,0]
	v_pk_mul_f32 v[158:159], v[116:117], s[22:23] op_sel_hi:[1,0]
	v_pk_mul_f32 v[160:161], v[114:115], s[22:23] op_sel_hi:[1,0]
	v_lshlrev_b32_e32 v114, 16, v154
	v_and_b32_e32 v115, 0xffff0000, v154
	v_lshlrev_b32_e32 v116, 16, v155
	v_and_b32_e32 v117, 0xffff0000, v155
	v_cvt_f32_i32_e32 v23, v23
	v_cvt_f32_i32_e32 v22, v22
	v_cvt_f32_i32_e32 v25, v25
	v_cvt_f32_i32_e32 v24, v24
	v_cvt_f32_i32_e32 v19, v19
	v_cvt_f32_i32_e32 v21, v21
	v_cvt_f32_i32_e32 v20, v20
	v_cvt_f32_i32_e32 v18, v18
	s_add_u32 s25, s77, 0xffffff00
	v_pk_mul_f32 v[114:115], v[122:123], v[114:115]
	v_pk_mul_f32 v[116:117], v[124:125], v[116:117]
	v_lshlrev_b32_e32 v122, 16, v156
	v_and_b32_e32 v123, 0xffff0000, v156
	v_lshlrev_b32_e32 v124, 16, v157
	v_and_b32_e32 v125, 0xffff0000, v157
	v_pk_mul_f32 v[128:129], v[128:129], s[22:23] op_sel_hi:[1,0]
	v_pk_mul_f32 v[126:127], v[126:127], s[22:23] op_sel_hi:[1,0]
	v_pk_mul_f32 v[154:155], v[120:121], s[22:23] op_sel_hi:[1,0]
	v_pk_mul_f32 v[156:157], v[118:119], s[22:23] op_sel_hi:[1,0]
	v_lshlrev_b32_e32 v118, 16, v150
	v_and_b32_e32 v119, 0xffff0000, v150
	v_lshlrev_b32_e32 v120, 16, v151
	v_and_b32_e32 v121, 0xffff0000, v151
	v_cvt_f32_i32_e32 v15, v15
	v_cvt_f32_i32_e32 v14, v14
	v_cvt_f32_i32_e32 v17, v17
	v_cvt_f32_i32_e32 v16, v16
	v_cvt_f32_i32_e32 v11, v11
	v_cvt_f32_i32_e32 v13, v13
	v_cvt_f32_i32_e32 v12, v12
	v_cvt_f32_i32_e32 v10, v10
	s_addc_u32 s40, s78, -1
	s_ashr_i32 s15, s14, 31
	v_pk_mul_f32 v[118:119], v[126:127], v[118:119]
	v_pk_mul_f32 v[120:121], v[128:129], v[120:121]
	v_lshlrev_b32_e32 v126, 16, v152
	v_and_b32_e32 v127, 0xffff0000, v152
	v_lshlrev_b32_e32 v128, 16, v153
	v_and_b32_e32 v129, 0xffff0000, v153
	v_pk_mul_f32 v[80:81], v[80:81], s[22:23] op_sel_hi:[1,0]
	v_pk_mul_f32 v[78:79], v[78:79], s[22:23] op_sel_hi:[1,0]
	v_pk_mul_f32 v[150:151], v[68:69], s[22:23] op_sel_hi:[1,0]
	v_pk_mul_f32 v[152:153], v[66:67], s[22:23] op_sel_hi:[1,0]
	v_lshlrev_b32_e32 v66, 16, v146
	v_and_b32_e32 v67, 0xffff0000, v146
	v_lshlrev_b32_e32 v68, 16, v147
	v_and_b32_e32 v69, 0xffff0000, v147
	v_cvt_f32_i32_e32 v7, v7
	v_cvt_f32_i32_e32 v6, v6
	v_cvt_f32_i32_e32 v9, v9
	v_cvt_f32_i32_e32 v8, v8
	v_cvt_f32_i32_e32 v3, v3
	v_cvt_f32_i32_e32 v5, v5
	v_cvt_f32_i32_e32 v4, v4
	v_cvt_f32_i32_e32 v2, v2
	s_and_b64 s[0:1], s[26:27], exec
	v_pk_mul_f32 v[66:67], v[78:79], v[66:67]
	v_pk_mul_f32 v[68:69], v[80:81], v[68:69]
	v_lshlrev_b32_e32 v78, 16, v148
	v_and_b32_e32 v79, 0xffff0000, v148
	v_lshlrev_b32_e32 v80, 16, v149
	v_and_b32_e32 v81, 0xffff0000, v149
	v_pk_mul_f32 v[64:65], v[64:65], s[22:23] op_sel_hi:[1,0]
	v_pk_mul_f32 v[62:63], v[62:63], s[22:23] op_sel_hi:[1,0]
	v_pk_mul_f32 v[146:147], v[52:53], s[22:23] op_sel_hi:[1,0]
	v_pk_mul_f32 v[148:149], v[50:51], s[22:23] op_sel_hi:[1,0]
	v_lshlrev_b32_e32 v50, 16, v142
	v_and_b32_e32 v51, 0xffff0000, v142
	v_lshlrev_b32_e32 v52, 16, v143
	v_and_b32_e32 v53, 0xffff0000, v143
	s_cselect_b32 s0, s39, s31
	s_cselect_b32 s1, s38, s30
	s_lshl_b64 s[14:15], s[14:15], 20
	v_readlane_b32 s30, v254, 41
	v_pk_mul_f32 v[50:51], v[62:63], v[50:51]
	v_pk_mul_f32 v[52:53], v[64:65], v[52:53]
	v_lshlrev_b32_e32 v62, 16, v144
	v_and_b32_e32 v63, 0xffff0000, v144
	v_lshlrev_b32_e32 v64, 16, v145
	v_and_b32_e32 v65, 0xffff0000, v145
	v_pk_mul_f32 v[24:25], v[24:25], s[22:23] op_sel_hi:[1,0]
	v_pk_mul_f32 v[22:23], v[22:23], s[22:23] op_sel_hi:[1,0]
	v_pk_mul_f32 v[142:143], v[20:21], s[22:23] op_sel_hi:[1,0]
	v_pk_mul_f32 v[144:145], v[18:19], s[22:23] op_sel_hi:[1,0]
	v_lshlrev_b32_e32 v18, 16, v138
	v_and_b32_e32 v19, 0xffff0000, v138
	v_lshlrev_b32_e32 v20, 16, v139
	v_and_b32_e32 v21, 0xffff0000, v139
	v_readlane_b32 s31, v254, 42
	s_add_u32 s36, s30, s14
	v_pk_mul_f32 v[18:19], v[22:23], v[18:19]
	v_pk_mul_f32 v[20:21], v[24:25], v[20:21]
	v_lshlrev_b32_e32 v22, 16, v140
	v_and_b32_e32 v23, 0xffff0000, v140
	v_lshlrev_b32_e32 v24, 16, v141
	v_and_b32_e32 v25, 0xffff0000, v141
	v_pk_mul_f32 v[16:17], v[16:17], s[22:23] op_sel_hi:[1,0]
	v_pk_mul_f32 v[14:15], v[14:15], s[22:23] op_sel_hi:[1,0]
	v_pk_mul_f32 v[138:139], v[12:13], s[22:23] op_sel_hi:[1,0]
	v_pk_mul_f32 v[140:141], v[10:11], s[22:23] op_sel_hi:[1,0]
	v_lshlrev_b32_e32 v10, 16, v134
	v_and_b32_e32 v11, 0xffff0000, v134
	v_lshlrev_b32_e32 v12, 16, v135
	v_and_b32_e32 v13, 0xffff0000, v135
	s_addc_u32 s37, s31, s15
	v_pk_mul_f32 v[10:11], v[14:15], v[10:11]
	v_pk_mul_f32 v[12:13], v[16:17], v[12:13]
	v_lshlrev_b32_e32 v14, 16, v136
	v_and_b32_e32 v15, 0xffff0000, v136
	v_lshlrev_b32_e32 v16, 16, v137
	v_and_b32_e32 v17, 0xffff0000, v137
	v_pk_mul_f32 v[8:9], v[8:9], s[22:23] op_sel_hi:[1,0]
	v_pk_mul_f32 v[6:7], v[6:7], s[22:23] op_sel_hi:[1,0]
	v_pk_mul_f32 v[134:135], v[4:5], s[22:23] op_sel_hi:[1,0]
	v_pk_mul_f32 v[136:137], v[2:3], s[22:23] op_sel_hi:[1,0]
	v_lshlrev_b32_e32 v2, 16, v130
	v_and_b32_e32 v3, 0xffff0000, v130
	v_lshlrev_b32_e32 v4, 16, v131
	v_and_b32_e32 v5, 0xffff0000, v131
	s_and_b64 s[14:15], s[26:27], exec
	v_pk_mul_f32 v[2:3], v[6:7], v[2:3]
	v_pk_mul_f32 v[4:5], v[8:9], v[4:5]
	v_lshlrev_b32_e32 v6, 16, v132
	v_and_b32_e32 v7, 0xffff0000, v132
	v_lshlrev_b32_e32 v8, 16, v133
	v_and_b32_e32 v9, 0xffff0000, v133
	s_cselect_b32 s14, s37, s40
	s_cselect_b32 s15, s36, s25
	s_add_u32 s25, s58, s2
	v_pk_mul_f32 v[30:31], v[240:241], v[30:31]
	v_pk_mul_f32 v[32:33], v[238:239], v[32:33]
	v_pk_mul_f32 v[38:39], v[192:193], v[38:39]
	v_pk_mul_f32 v[40:41], v[190:191], v[40:41]
	v_pk_mul_f32 v[46:47], v[188:189], v[46:47]
	v_pk_mul_f32 v[48:49], v[186:187], v[48:49]
	v_pk_mul_f32 v[58:59], v[184:185], v[58:59]
	v_pk_mul_f32 v[60:61], v[182:183], v[60:61]
	v_pk_mul_f32 v[74:75], v[180:181], v[74:75]
	v_pk_mul_f32 v[76:77], v[178:179], v[76:77]
	v_pk_mul_f32 v[86:87], v[176:177], v[86:87]
	v_pk_mul_f32 v[88:89], v[174:175], v[88:89]
	v_pk_mul_f32 v[94:95], v[172:173], v[94:95]
	v_pk_mul_f32 v[96:97], v[170:171], v[96:97]
	v_pk_mul_f32 v[102:103], v[168:169], v[102:103]
	v_pk_mul_f32 v[104:105], v[166:167], v[104:105]
	v_pk_mul_f32 v[110:111], v[164:165], v[110:111]
	v_pk_mul_f32 v[112:113], v[162:163], v[112:113]
	v_pk_mul_f32 v[122:123], v[160:161], v[122:123]
	v_pk_mul_f32 v[124:125], v[158:159], v[124:125]
	v_pk_mul_f32 v[126:127], v[156:157], v[126:127]
	v_pk_mul_f32 v[128:129], v[154:155], v[128:129]
	v_pk_mul_f32 v[78:79], v[152:153], v[78:79]
	v_pk_mul_f32 v[80:81], v[150:151], v[80:81]
	v_pk_mul_f32 v[62:63], v[148:149], v[62:63]
	v_pk_mul_f32 v[64:65], v[146:147], v[64:65]
	v_pk_mul_f32 v[22:23], v[144:145], v[22:23]
	v_pk_mul_f32 v[24:25], v[142:143], v[24:25]
	v_pk_mul_f32 v[14:15], v[140:141], v[14:15]
	v_pk_mul_f32 v[16:17], v[138:139], v[16:17]
	v_pk_mul_f32 v[6:7], v[136:137], v[6:7]
	v_pk_mul_f32 v[8:9], v[134:135], v[8:9]
	v_lshl_add_u64 v[130:131], v[220:221], 0, s[34:35]
	v_lshl_add_u64 v[132:133], v[222:223], 0, s[34:35]
	s_addc_u32 s40, s59, s3
	s_mov_b32 s41, -2
	s_mov_b64 s[2:3], 0
	.p2alignl 8, 3212836864

.LBB0_816:
	s_mov_b32 s75, s74
	s_add_i32 s74, s74, 1
	s_cmp_lt_u32 s75, 3
	s_cselect_b64 s[86:87], -1, 0
	s_lshl_b32 s6, s74, 4
	s_or_b32 s20, s6, s54
	s_lshl_b64 s[6:7], s[20:21], 21
	v_readlane_b32 s8, v254, 52
	v_readlane_b32 s9, v254, 53
	s_add_u32 s8, s8, s6
	s_addc_u32 s9, s9, s7
	s_mov_b64 s[0:1], s[78:79]
	s_mov_b64 s[4:5], s[18:19]
	s_and_b64 s[6:7], s[86:87], exec
	s_cselect_b32 s19, s9, s5
	s_cselect_b32 s18, s8, s4
	s_cselect_b32 s79, s3, s1
	s_cselect_b32 s78, s2, s0
	s_add_u32 s4, s4, 0x100080
	s_addc_u32 s5, s5, 0
	s_add_u32 s0, s0, 0x100
	v_mov_b32_e32 v126, 0
	s_addc_u32 s1, s1, 0
	s_mov_b32 s14, -2
	v_mov_b32_e32 v127, v126
	v_mov_b32_e32 v128, v126
	v_mov_b32_e32 v129, v126
	v_mov_b32_e32 v122, v126
	v_mov_b32_e32 v123, v126
	v_mov_b32_e32 v124, v126
	v_mov_b32_e32 v125, v126
	v_mov_b32_e32 v98, v126
	v_mov_b32_e32 v99, v126
	v_mov_b32_e32 v100, v126
	v_mov_b32_e32 v101, v126
	v_mov_b32_e32 v102, v126
	v_mov_b32_e32 v103, v126
	v_mov_b32_e32 v104, v126
	v_mov_b32_e32 v105, v126
	v_mov_b32_e32 v82, v126
	v_mov_b32_e32 v83, v126
	v_mov_b32_e32 v84, v126
	v_mov_b32_e32 v85, v126
	v_mov_b32_e32 v86, v126
	v_mov_b32_e32 v87, v126
	v_mov_b32_e32 v88, v126
	v_mov_b32_e32 v89, v126
	v_mov_b32_e32 v66, v126
	v_mov_b32_e32 v67, v126
	v_mov_b32_e32 v68, v126
	v_mov_b32_e32 v69, v126
	v_mov_b32_e32 v70, v126
	v_mov_b32_e32 v71, v126
	v_mov_b32_e32 v72, v126
	v_mov_b32_e32 v73, v126
	v_mov_b32_e32 v114, v126
	v_mov_b32_e32 v115, v126
	v_mov_b32_e32 v116, v126
	v_mov_b32_e32 v117, v126
	v_mov_b32_e32 v118, v126
	v_mov_b32_e32 v119, v126
	v_mov_b32_e32 v120, v126
	v_mov_b32_e32 v121, v126
	v_mov_b32_e32 v106, v126
	v_mov_b32_e32 v107, v126
	v_mov_b32_e32 v108, v126
	v_mov_b32_e32 v109, v126
	v_mov_b32_e32 v110, v126
	v_mov_b32_e32 v111, v126
	v_mov_b32_e32 v112, v126
	v_mov_b32_e32 v113, v126
	v_mov_b32_e32 v90, v126
	v_mov_b32_e32 v91, v126
	v_mov_b32_e32 v92, v126
	v_mov_b32_e32 v93, v126
	v_mov_b32_e32 v94, v126
	v_mov_b32_e32 v95, v126
	v_mov_b32_e32 v96, v126
	v_mov_b32_e32 v97, v126
	v_mov_b32_e32 v74, v126
	v_mov_b32_e32 v75, v126
	v_mov_b32_e32 v76, v126
	v_mov_b32_e32 v77, v126
	v_mov_b32_e32 v78, v126
	v_mov_b32_e32 v79, v126
	v_mov_b32_e32 v80, v126
	v_mov_b32_e32 v81, v126
	v_mov_b32_e32 v50, v126
	v_mov_b32_e32 v51, v126
	v_mov_b32_e32 v52, v126
	v_mov_b32_e32 v53, v126
	v_mov_b32_e32 v54, v126
	v_mov_b32_e32 v55, v126
	v_mov_b32_e32 v56, v126
	v_mov_b32_e32 v57, v126
	v_mov_b32_e32 v30, v126
	v_mov_b32_e32 v31, v126
	v_mov_b32_e32 v32, v126
	v_mov_b32_e32 v33, v126
	v_mov_b32_e32 v38, v126
	v_mov_b32_e32 v39, v126
	v_mov_b32_e32 v40, v126
	v_mov_b32_e32 v41, v126
	v_mov_b32_e32 v18, v126
	v_mov_b32_e32 v19, v126
	v_mov_b32_e32 v20, v126
	v_mov_b32_e32 v21, v126
	v_mov_b32_e32 v22, v126
	v_mov_b32_e32 v23, v126
	v_mov_b32_e32 v24, v126
	v_mov_b32_e32 v25, v126
	v_mov_b32_e32 v2, v126
	v_mov_b32_e32 v3, v126
	v_mov_b32_e32 v4, v126
	v_mov_b32_e32 v5, v126
	v_mov_b32_e32 v6, v126
	v_mov_b32_e32 v7, v126
	v_mov_b32_e32 v8, v126
	v_mov_b32_e32 v9, v126
	v_mov_b32_e32 v58, v126
	v_mov_b32_e32 v59, v126
	v_mov_b32_e32 v60, v126
	v_mov_b32_e32 v61, v126
	v_mov_b32_e32 v62, v126
	v_mov_b32_e32 v63, v126
	v_mov_b32_e32 v64, v126
	v_mov_b32_e32 v65, v126
	v_mov_b32_e32 v42, v126
	v_mov_b32_e32 v43, v126
	v_mov_b32_e32 v44, v126
	v_mov_b32_e32 v45, v126
	v_mov_b32_e32 v46, v126
	v_mov_b32_e32 v47, v126
	v_mov_b32_e32 v48, v126
	v_mov_b32_e32 v49, v126
	v_mov_b32_e32 v26, v126
	v_mov_b32_e32 v27, v126
	v_mov_b32_e32 v28, v126
	v_mov_b32_e32 v29, v126
	v_mov_b32_e32 v34, v126
	v_mov_b32_e32 v35, v126
	v_mov_b32_e32 v36, v126
	v_mov_b32_e32 v37, v126
	v_mov_b32_e32 v10, v126
	v_mov_b32_e32 v11, v126
	v_mov_b32_e32 v12, v126
	v_mov_b32_e32 v13, v126
	v_mov_b32_e32 v14, v126
	v_mov_b32_e32 v15, v126
	v_mov_b32_e32 v16, v126
	v_mov_b32_e32 v17, v126
	.p2alignl 8, 3212836864

.LBB0_960:
	s_ashr_i32 s19, s18, 31
	s_ashr_i32 s15, s14, 31
	s_lshl_b64 s[22:23], s[18:19], 20
	s_lshl_b64 s[24:25], s[14:15], 20
	v_readlane_b32 s34, v254, 39
	v_readlane_b32 s35, v254, 40
	s_add_u32 s22, s34, s22
	s_addc_u32 s23, s35, s23
	s_add_u32 s24, s52, s24
	s_addc_u32 s25, s53, s25
	s_and_b64 s[34:35], s[20:21], exec
	s_cselect_b32 s1, s23, s29
	s_cselect_b32 s15, s22, s28
	s_cselect_b32 s19, s25, s31
	s_cselect_b32 s42, s24, s30
	s_add_u32 s28, s28, 0x80080
	s_addc_u32 s29, s29, 0
	s_add_u32 s43, s30, 0x100
	v_mov_b32_e32 v2, 0
	s_addc_u32 s44, s31, 0
	s_mov_b32 s45, -2
	v_mov_b32_e32 v3, v2
	v_mov_b32_e32 v4, v2
	v_mov_b32_e32 v5, v2
	v_mov_b32_e32 v6, v2
	v_mov_b32_e32 v7, v2
	v_mov_b32_e32 v8, v2
	v_mov_b32_e32 v9, v2
	v_mov_b32_e32 v18, v2
	v_mov_b32_e32 v19, v2
	v_mov_b32_e32 v20, v2
	v_mov_b32_e32 v21, v2
	v_mov_b32_e32 v22, v2
	v_mov_b32_e32 v23, v2
	v_mov_b32_e32 v24, v2
	v_mov_b32_e32 v25, v2
	v_mov_b32_e32 v34, v2
	v_mov_b32_e32 v35, v2
	v_mov_b32_e32 v36, v2
	v_mov_b32_e32 v37, v2
	v_mov_b32_e32 v38, v2
	v_mov_b32_e32 v39, v2
	v_mov_b32_e32 v40, v2
	v_mov_b32_e32 v41, v2
	v_mov_b32_e32 v50, v2
	v_mov_b32_e32 v51, v2
	v_mov_b32_e32 v52, v2
	v_mov_b32_e32 v53, v2
	v_mov_b32_e32 v54, v2
	v_mov_b32_e32 v55, v2
	v_mov_b32_e32 v56, v2
	v_mov_b32_e32 v57, v2
	v_mov_b32_e32 v10, v2
	v_mov_b32_e32 v11, v2
	v_mov_b32_e32 v12, v2
	v_mov_b32_e32 v13, v2
	v_mov_b32_e32 v14, v2
	v_mov_b32_e32 v15, v2
	v_mov_b32_e32 v16, v2
	v_mov_b32_e32 v17, v2
	v_mov_b32_e32 v26, v2
	v_mov_b32_e32 v27, v2
	v_mov_b32_e32 v28, v2
	v_mov_b32_e32 v29, v2
	v_mov_b32_e32 v30, v2
	v_mov_b32_e32 v31, v2
	v_mov_b32_e32 v32, v2
	v_mov_b32_e32 v33, v2
	v_mov_b32_e32 v42, v2
	v_mov_b32_e32 v43, v2
	v_mov_b32_e32 v44, v2
	v_mov_b32_e32 v45, v2
	v_mov_b32_e32 v46, v2
	v_mov_b32_e32 v47, v2
	v_mov_b32_e32 v48, v2
	v_mov_b32_e32 v49, v2
	v_mov_b32_e32 v58, v2
	v_mov_b32_e32 v59, v2
	v_mov_b32_e32 v60, v2
	v_mov_b32_e32 v61, v2
	v_mov_b32_e32 v62, v2
	v_mov_b32_e32 v63, v2
	v_mov_b32_e32 v64, v2
	v_mov_b32_e32 v65, v2
	v_mov_b32_e32 v66, v2
	v_mov_b32_e32 v67, v2
	v_mov_b32_e32 v68, v2
	v_mov_b32_e32 v69, v2
	v_mov_b32_e32 v70, v2
	v_mov_b32_e32 v71, v2
	v_mov_b32_e32 v72, v2
	v_mov_b32_e32 v73, v2
	v_mov_b32_e32 v82, v2
	v_mov_b32_e32 v83, v2
	v_mov_b32_e32 v84, v2
	v_mov_b32_e32 v85, v2
	v_mov_b32_e32 v86, v2
	v_mov_b32_e32 v87, v2
	v_mov_b32_e32 v88, v2
	v_mov_b32_e32 v89, v2
	v_mov_b32_e32 v98, v2
	v_mov_b32_e32 v99, v2
	v_mov_b32_e32 v100, v2
	v_mov_b32_e32 v101, v2
	v_mov_b32_e32 v102, v2
	v_mov_b32_e32 v103, v2
	v_mov_b32_e32 v104, v2
	v_mov_b32_e32 v105, v2
	v_mov_b32_e32 v114, v2
	v_mov_b32_e32 v115, v2
	v_mov_b32_e32 v116, v2
	v_mov_b32_e32 v117, v2
	v_mov_b32_e32 v118, v2
	v_mov_b32_e32 v119, v2
	v_mov_b32_e32 v120, v2
	v_mov_b32_e32 v121, v2
	v_mov_b32_e32 v74, v2
	v_mov_b32_e32 v75, v2
	v_mov_b32_e32 v76, v2
	v_mov_b32_e32 v77, v2
	v_mov_b32_e32 v78, v2
	v_mov_b32_e32 v79, v2
	v_mov_b32_e32 v80, v2
	v_mov_b32_e32 v81, v2
	v_mov_b32_e32 v90, v2
	v_mov_b32_e32 v91, v2
	v_mov_b32_e32 v92, v2
	v_mov_b32_e32 v93, v2
	v_mov_b32_e32 v94, v2
	v_mov_b32_e32 v95, v2
	v_mov_b32_e32 v96, v2
	v_mov_b32_e32 v97, v2
	v_mov_b32_e32 v106, v2
	v_mov_b32_e32 v107, v2
	v_mov_b32_e32 v108, v2
	v_mov_b32_e32 v109, v2
	v_mov_b32_e32 v110, v2
	v_mov_b32_e32 v111, v2
	v_mov_b32_e32 v112, v2
	v_mov_b32_e32 v113, v2
	v_mov_b32_e32 v122, v2
	v_mov_b32_e32 v123, v2
	v_mov_b32_e32 v124, v2
	v_mov_b32_e32 v125, v2
	v_mov_b32_e32 v126, v2
	v_mov_b32_e32 v127, v2
	v_mov_b32_e32 v128, v2
	v_mov_b32_e32 v129, v2
	.p2alignl 8, 3212836864

.LBB0_1057:
	s_add_u32 s29, s6, 0x100
	v_mov_b32_e32 v112, 0
	s_addc_u32 s38, s7, 0
	s_mov_b32 s39, -2
	v_mov_b32_e32 v113, v112
	v_mov_b32_e32 v114, v112
	v_mov_b32_e32 v115, v112
	v_mov_b32_e32 v116, v112
	v_mov_b32_e32 v117, v112
	v_mov_b32_e32 v118, v112
	v_mov_b32_e32 v119, v112
	v_mov_b32_e32 v96, v112
	v_mov_b32_e32 v97, v112
	v_mov_b32_e32 v98, v112
	v_mov_b32_e32 v99, v112
	v_mov_b32_e32 v100, v112
	v_mov_b32_e32 v101, v112
	v_mov_b32_e32 v102, v112
	v_mov_b32_e32 v103, v112
	v_mov_b32_e32 v80, v112
	v_mov_b32_e32 v81, v112
	v_mov_b32_e32 v82, v112
	v_mov_b32_e32 v83, v112
	v_mov_b32_e32 v84, v112
	v_mov_b32_e32 v85, v112
	v_mov_b32_e32 v86, v112
	v_mov_b32_e32 v87, v112
	v_mov_b32_e32 v60, v112
	v_mov_b32_e32 v61, v112
	v_mov_b32_e32 v62, v112
	v_mov_b32_e32 v63, v112
	v_mov_b32_e32 v68, v112
	v_mov_b32_e32 v69, v112
	v_mov_b32_e32 v70, v112
	v_mov_b32_e32 v71, v112
	v_mov_b32_e32 v120, v112
	v_mov_b32_e32 v121, v112
	v_mov_b32_e32 v122, v112
	v_mov_b32_e32 v123, v112
	v_mov_b32_e32 v124, v112
	v_mov_b32_e32 v125, v112
	v_mov_b32_e32 v126, v112
	v_mov_b32_e32 v127, v112
	v_mov_b32_e32 v104, v112
	v_mov_b32_e32 v105, v112
	v_mov_b32_e32 v106, v112
	v_mov_b32_e32 v107, v112
	v_mov_b32_e32 v108, v112
	v_mov_b32_e32 v109, v112
	v_mov_b32_e32 v110, v112
	v_mov_b32_e32 v111, v112
	v_mov_b32_e32 v88, v112
	v_mov_b32_e32 v89, v112
	v_mov_b32_e32 v90, v112
	v_mov_b32_e32 v91, v112
	v_mov_b32_e32 v92, v112
	v_mov_b32_e32 v93, v112
	v_mov_b32_e32 v94, v112
	v_mov_b32_e32 v95, v112
	v_mov_b32_e32 v72, v112
	v_mov_b32_e32 v73, v112
	v_mov_b32_e32 v74, v112
	v_mov_b32_e32 v75, v112
	v_mov_b32_e32 v76, v112
	v_mov_b32_e32 v77, v112
	v_mov_b32_e32 v78, v112
	v_mov_b32_e32 v79, v112
	v_mov_b32_e32 v48, v112
	v_mov_b32_e32 v49, v112
	v_mov_b32_e32 v50, v112
	v_mov_b32_e32 v51, v112
	v_mov_b32_e32 v52, v112
	v_mov_b32_e32 v53, v112
	v_mov_b32_e32 v54, v112
	v_mov_b32_e32 v55, v112
	v_mov_b32_e32 v20, v112
	v_mov_b32_e32 v21, v112
	v_mov_b32_e32 v22, v112
	v_mov_b32_e32 v23, v112
	v_mov_b32_e32 v28, v112
	v_mov_b32_e32 v29, v112
	v_mov_b32_e32 v30, v112
	v_mov_b32_e32 v31, v112
	v_mov_b32_e32 v16, v112
	v_mov_b32_e32 v17, v112
	v_mov_b32_e32 v18, v112
	v_mov_b32_e32 v19, v112
	v_mov_b32_e32 v24, v112
	v_mov_b32_e32 v25, v112
	v_mov_b32_e32 v26, v112
	v_mov_b32_e32 v27, v112
	v_mov_b32_e32 v0, v112
	v_mov_b32_e32 v1, v112
	v_mov_b32_e32 v2, v112
	v_mov_b32_e32 v3, v112
	v_mov_b32_e32 v4, v112
	v_mov_b32_e32 v5, v112
	v_mov_b32_e32 v6, v112
	v_mov_b32_e32 v7, v112
	v_mov_b32_e32 v56, v112
	v_mov_b32_e32 v57, v112
	v_mov_b32_e32 v58, v112
	v_mov_b32_e32 v59, v112
	v_mov_b32_e32 v64, v112
	v_mov_b32_e32 v65, v112
	v_mov_b32_e32 v66, v112
	v_mov_b32_e32 v67, v112
	v_mov_b32_e32 v40, v112
	v_mov_b32_e32 v41, v112
	v_mov_b32_e32 v42, v112
	v_mov_b32_e32 v43, v112
	v_mov_b32_e32 v44, v112
	v_mov_b32_e32 v45, v112
	v_mov_b32_e32 v46, v112
	v_mov_b32_e32 v47, v112
	v_mov_b32_e32 v32, v112
	v_mov_b32_e32 v33, v112
	v_mov_b32_e32 v34, v112
	v_mov_b32_e32 v35, v112
	v_mov_b32_e32 v36, v112
	v_mov_b32_e32 v37, v112
	v_mov_b32_e32 v38, v112
	v_mov_b32_e32 v39, v112
	v_mov_b32_e32 v8, v112
	v_mov_b32_e32 v9, v112
	v_mov_b32_e32 v10, v112
	v_mov_b32_e32 v11, v112
	v_mov_b32_e32 v12, v112
	v_mov_b32_e32 v13, v112
	v_mov_b32_e32 v14, v112
	v_mov_b32_e32 v15, v112
	.p2alignl 8, 3212836864
